# residual+norm epilogue: XB piece reads pipelined one group ahead through two spare quads; the 8 row rstd values read once after the exchange barrier
# speedup vs baseline: 1.0008x; 1.0008x over previous
.Lcab_nomods:
	v_and_b32_e32 v0, 63, v163
	v_lshlrev_b32_e32 v130, 4, v0
	s_mov_b64 s[12:13], -1
	s_and_b64 vcc, exec, s[38:39]
	v_add_u32_e32 v165, s7, v130
	s_cbranch_vccz .LBB0_784
	s_waitcnt vmcnt(0)
	ds_read_b128 v[228:231], v165 offset:8192
	ds_read_b128 v[232:235], v165 offset:9216
	s_mov_b64 s[12:13], 0
	s_waitcnt lgkmcnt(1)
	v_lshlrev_b32_e32 v138, 16, v228
	v_and_b32_e32 v139, 0xffff0000, v228
	v_lshlrev_b32_e32 v140, 16, v229
	v_and_b32_e32 v141, 0xffff0000, v229
	v_lshlrev_b32_e32 v130, 16, v230
	v_and_b32_e32 v131, 0xffff0000, v230
	v_lshlrev_b32_e32 v132, 16, v231
	v_and_b32_e32 v133, 0xffff0000, v231

.LBB0_788:
	s_and_b64 vcc, exec, s[10:11]
	s_mov_b64 s[12:13], -1
	s_cbranch_vccnz .LBB0_790
	ds_read_b128 v[228:231], v165 offset:10240
	s_waitcnt lgkmcnt(1)
	v_lshlrev_b32_e32 v126, 16, v232
	v_and_b32_e32 v127, 0xffff0000, v232
	v_lshlrev_b32_e32 v128, 16, v233
	v_and_b32_e32 v129, 0xffff0000, v233
	v_lshlrev_b32_e32 v122, 16, v234
	v_and_b32_e32 v123, 0xffff0000, v234
	v_lshlrev_b32_e32 v124, 16, v235
	v_and_b32_e32 v125, 0xffff0000, v235
	s_cbranch_execz .LBB0_791
	s_branch .LBB0_792

.LBB0_794:
	s_and_b64 vcc, exec, s[10:11]
	s_mov_b64 s[12:13], -1
	s_cbranch_vccnz .LBB0_796
	ds_read_b128 v[232:235], v165 offset:11264
	s_waitcnt lgkmcnt(1)
	v_lshlrev_b32_e32 v118, 16, v228
	v_and_b32_e32 v119, 0xffff0000, v228
	v_lshlrev_b32_e32 v120, 16, v229
	v_and_b32_e32 v121, 0xffff0000, v229
	v_lshlrev_b32_e32 v114, 16, v230
	v_and_b32_e32 v115, 0xffff0000, v230
	v_lshlrev_b32_e32 v116, 16, v231
	v_and_b32_e32 v117, 0xffff0000, v231
	s_cbranch_execz .LBB0_797
	s_branch .LBB0_798

.LBB0_800:
	s_and_b64 vcc, exec, s[10:11]
	s_mov_b64 s[12:13], -1
	s_cbranch_vccnz .LBB0_802
	ds_read_b128 v[228:231], v165 offset:12288
	s_waitcnt lgkmcnt(1)
	v_lshlrev_b32_e32 v110, 16, v232
	v_and_b32_e32 v111, 0xffff0000, v232
	v_lshlrev_b32_e32 v112, 16, v233
	v_and_b32_e32 v113, 0xffff0000, v233
	v_lshlrev_b32_e32 v106, 16, v234
	v_and_b32_e32 v107, 0xffff0000, v234
	v_lshlrev_b32_e32 v108, 16, v235
	v_and_b32_e32 v109, 0xffff0000, v235
	s_cbranch_execz .LBB0_803
	s_branch .LBB0_804

.LBB0_806:
	s_and_b64 vcc, exec, s[10:11]
	s_mov_b64 s[12:13], -1
	s_cbranch_vccnz .LBB0_808
	ds_read_b128 v[232:235], v165 offset:13312
	s_mov_b64 s[12:13], 0
	s_waitcnt lgkmcnt(1)
	v_lshlrev_b32_e32 v102, 16, v228
	v_and_b32_e32 v103, 0xffff0000, v228
	v_lshlrev_b32_e32 v104, 16, v229
	v_and_b32_e32 v105, 0xffff0000, v229
	v_lshlrev_b32_e32 v98, 16, v230
	v_and_b32_e32 v99, 0xffff0000, v230
	v_lshlrev_b32_e32 v100, 16, v231
	v_and_b32_e32 v101, 0xffff0000, v231

.LBB0_812:
	s_and_b64 vcc, exec, s[10:11]
	s_mov_b64 s[12:13], -1
	s_cbranch_vccnz .LBB0_814
	ds_read_b128 v[228:231], v165 offset:14336
	s_waitcnt lgkmcnt(1)
	v_lshlrev_b32_e32 v94, 16, v232
	v_and_b32_e32 v95, 0xffff0000, v232
	v_lshlrev_b32_e32 v96, 16, v233
	v_and_b32_e32 v97, 0xffff0000, v233
	v_lshlrev_b32_e32 v90, 16, v234
	v_and_b32_e32 v91, 0xffff0000, v234
	v_lshlrev_b32_e32 v92, 16, v235
	v_and_b32_e32 v93, 0xffff0000, v235
	s_cbranch_execz .LBB0_815
	s_branch .LBB0_816

.LBB0_818:
	s_and_b64 vcc, exec, s[10:11]
	s_mov_b64 s[12:13], -1
	s_cbranch_vccnz .LBB0_820
	ds_read_b128 v[232:235], v165 offset:15360
	s_waitcnt lgkmcnt(1)
	v_lshlrev_b32_e32 v86, 16, v228
	v_and_b32_e32 v87, 0xffff0000, v228
	v_lshlrev_b32_e32 v88, 16, v229
	v_and_b32_e32 v89, 0xffff0000, v229
	v_lshlrev_b32_e32 v82, 16, v230
	v_and_b32_e32 v83, 0xffff0000, v230
	v_lshlrev_b32_e32 v84, 16, v231
	v_and_b32_e32 v85, 0xffff0000, v231
	s_cbranch_execz .LBB0_821
	s_branch .LBB0_822

.LBB0_824:
	s_and_b64 vcc, exec, s[10:11]
	s_mov_b64 s[12:13], -1
	s_cbranch_vccnz .LBB0_826
	ds_read_b128 v[228:231], v165 offset:16384
	s_waitcnt lgkmcnt(1)
	v_lshlrev_b32_e32 v78, 16, v232
	v_and_b32_e32 v79, 0xffff0000, v232
	v_lshlrev_b32_e32 v80, 16, v233
	v_and_b32_e32 v81, 0xffff0000, v233
	v_lshlrev_b32_e32 v74, 16, v234
	v_and_b32_e32 v75, 0xffff0000, v234
	v_lshlrev_b32_e32 v76, 16, v235
	v_and_b32_e32 v77, 0xffff0000, v235
	s_cbranch_execz .LBB0_827
	s_branch .LBB0_828

.LBB0_830:
	v_mov_b64_e32 v[70:71], v[168:169]
	v_mov_b64_e32 v[72:73], v[170:171]
	v_mov_b64_e32 v[78:79], v[172:173]
	v_mov_b64_e32 v[80:81], v[174:175]
	s_and_b64 vcc, exec, s[10:11]
	s_mov_b64 s[12:13], -1
	s_cbranch_vccnz .LBB0_832
	ds_read_b128 v[232:235], v165 offset:17408
	s_mov_b64 s[12:13], 0
	s_waitcnt lgkmcnt(1)
	v_lshlrev_b32_e32 v74, 16, v228
	v_and_b32_e32 v75, 0xffff0000, v228
	v_lshlrev_b32_e32 v76, 16, v229
	v_and_b32_e32 v77, 0xffff0000, v229
	v_lshlrev_b32_e32 v62, 16, v230
	v_and_b32_e32 v63, 0xffff0000, v230
	v_lshlrev_b32_e32 v64, 16, v231
	v_and_b32_e32 v65, 0xffff0000, v231

.LBB0_836:
	s_and_b64 vcc, exec, s[10:11]
	s_mov_b64 s[12:13], -1
	s_cbranch_vccnz .LBB0_838
	ds_read_b128 v[228:231], v165 offset:18432
	s_waitcnt lgkmcnt(1)
	v_lshlrev_b32_e32 v62, 16, v232
	v_and_b32_e32 v63, 0xffff0000, v232
	v_lshlrev_b32_e32 v64, 16, v233
	v_and_b32_e32 v65, 0xffff0000, v233
	v_lshlrev_b32_e32 v58, 16, v234
	v_and_b32_e32 v59, 0xffff0000, v234
	v_lshlrev_b32_e32 v60, 16, v235
	v_and_b32_e32 v61, 0xffff0000, v235
	s_cbranch_execz .LBB0_839
	s_branch .LBB0_840

.LBB0_842:
	s_and_b64 vcc, exec, s[10:11]
	s_mov_b64 s[12:13], -1
	s_cbranch_vccnz .LBB0_844
	ds_read_b128 v[232:235], v165 offset:19456
	s_waitcnt lgkmcnt(1)
	v_lshlrev_b32_e32 v54, 16, v228
	v_and_b32_e32 v55, 0xffff0000, v228
	v_lshlrev_b32_e32 v56, 16, v229
	v_and_b32_e32 v57, 0xffff0000, v229
	v_lshlrev_b32_e32 v50, 16, v230
	v_and_b32_e32 v51, 0xffff0000, v230
	v_lshlrev_b32_e32 v52, 16, v231
	v_and_b32_e32 v53, 0xffff0000, v231
	s_cbranch_execz .LBB0_845
	s_branch .LBB0_846

.LBB0_848:
	s_and_b64 vcc, exec, s[10:11]
	s_mov_b64 s[12:13], -1
	s_cbranch_vccnz .LBB0_850
	ds_read_b128 v[228:231], v165 offset:20480
	s_waitcnt lgkmcnt(1)
	v_lshlrev_b32_e32 v46, 16, v232
	v_and_b32_e32 v47, 0xffff0000, v232
	v_lshlrev_b32_e32 v48, 16, v233
	v_and_b32_e32 v49, 0xffff0000, v233
	v_lshlrev_b32_e32 v42, 16, v234
	v_and_b32_e32 v43, 0xffff0000, v234
	v_lshlrev_b32_e32 v44, 16, v235
	v_and_b32_e32 v45, 0xffff0000, v235
	s_cbranch_execz .LBB0_851
	s_branch .LBB0_852

.LBB0_854:
	s_and_b64 vcc, exec, s[10:11]
	s_mov_b64 s[12:13], -1
	s_cbranch_vccnz .LBB0_856
	ds_read_b128 v[232:235], v165 offset:21504
	s_mov_b64 s[12:13], 0
	s_waitcnt lgkmcnt(1)
	v_lshlrev_b32_e32 v38, 16, v228
	v_and_b32_e32 v39, 0xffff0000, v228
	v_lshlrev_b32_e32 v40, 16, v229
	v_and_b32_e32 v41, 0xffff0000, v229
	v_lshlrev_b32_e32 v34, 16, v230
	v_and_b32_e32 v35, 0xffff0000, v230
	v_lshlrev_b32_e32 v36, 16, v231
	v_and_b32_e32 v37, 0xffff0000, v231

.LBB0_860:
	s_and_b64 vcc, exec, s[10:11]
	s_mov_b64 s[12:13], -1
	s_cbranch_vccnz .LBB0_862
	ds_read_b128 v[228:231], v165 offset:22528
	s_waitcnt lgkmcnt(1)
	v_lshlrev_b32_e32 v30, 16, v232
	v_and_b32_e32 v31, 0xffff0000, v232
	v_lshlrev_b32_e32 v32, 16, v233
	v_and_b32_e32 v33, 0xffff0000, v233
	v_lshlrev_b32_e32 v26, 16, v234
	v_and_b32_e32 v27, 0xffff0000, v234
	v_lshlrev_b32_e32 v28, 16, v235
	v_and_b32_e32 v29, 0xffff0000, v235
	s_cbranch_execz .LBB0_863
	s_branch .LBB0_864

.LBB0_866:
	s_and_b64 vcc, exec, s[10:11]
	s_mov_b64 s[12:13], -1
	s_cbranch_vccnz .LBB0_868
	ds_read_b128 v[232:235], v165 offset:23552
	s_waitcnt lgkmcnt(1)
	v_lshlrev_b32_e32 v22, 16, v228
	v_and_b32_e32 v23, 0xffff0000, v228
	v_lshlrev_b32_e32 v24, 16, v229
	v_and_b32_e32 v25, 0xffff0000, v229
	v_lshlrev_b32_e32 v18, 16, v230
	v_and_b32_e32 v19, 0xffff0000, v230
	v_lshlrev_b32_e32 v20, 16, v231
	v_and_b32_e32 v21, 0xffff0000, v231
	s_cbranch_execz .LBB0_869
	s_branch .LBB0_870

.LBB0_872:
	s_and_b64 vcc, exec, s[10:11]
	s_mov_b64 s[10:11], -1
	s_cbranch_vccnz .LBB0_874
	s_waitcnt lgkmcnt(0)
	v_lshlrev_b32_e32 v14, 16, v232
	v_and_b32_e32 v15, 0xffff0000, v232
	v_lshlrev_b32_e32 v16, 16, v233
	v_and_b32_e32 v17, 0xffff0000, v233
	v_lshlrev_b32_e32 v10, 16, v234
	v_and_b32_e32 v11, 0xffff0000, v234
	v_lshlrev_b32_e32 v12, 16, v235
	v_and_b32_e32 v13, 0xffff0000, v235
	s_cbranch_execz .LBB0_875
	s_branch .LBB0_876

.LBB0_903:
	s_or_b64 exec, exec, s[34:35]
	s_waitcnt lgkmcnt(0)
	s_barrier
	v_lshl_add_u32 v217, v162, 2, 0
	ds_read_b32 v228, v217 offset:4096
	ds_read_b32 v229, v217 offset:4160
	ds_read_b32 v230, v217 offset:4224
	ds_read_b32 v231, v217 offset:4288
	ds_read_b32 v232, v217 offset:4608
	ds_read_b32 v233, v217 offset:4672
	ds_read_b32 v234, v217 offset:4736
	ds_read_b32 v235, v217 offset:4800
	v_lshl_add_u64 v[158:159], v[148:149], 2, s[36:37]
	v_mov_b64_e32 v[2:3], v[176:177]
	v_mov_b64_e32 v[4:5], v[178:179]
	v_mov_b64_e32 v[6:7], v[180:181]
	v_mov_b64_e32 v[8:9], v[182:183]
	v_readlane_b32 s12, v255, 5
	v_readlane_b32 s13, v255, 4
	s_add_u32 s6, s72, s12
	s_addc_u32 s7, s73, 0
	s_lshl_b32 s10, s13, 2
	s_add_u32 s6, s6, s10
	s_addc_u32 s7, s7, 0
	s_add_u32 s4, s6, s4
	s_addc_u32 s5, s7, s5
	s_add_u32 s6, s4, 0x1000
	s_addc_u32 s7, s5, 0
	v_lshlrev_b64 v[12:13], 2, v[148:149]
	v_mov_b32_e32 v10, 0
	s_and_b64 vcc, exec, s[30:31]
	v_lshl_add_u64 v[160:161], s[6:7], 0, v[12:13]
	v_lshl_add_u64 v[150:151], s[4:5], 0, v[12:13]
	s_cbranch_vccz .LBB0_905
	v_mov_b64_e32 v[10:11], v[192:193]
	v_mov_b64_e32 v[12:13], v[194:195]
	v_mov_b64_e32 v[14:15], v[196:197]
	v_mov_b64_e32 v[16:17], v[198:199]
	v_pk_add_f32 v[12:13], v[12:13], 1.0 op_sel_hi:[1,0]
	v_pk_add_f32 v[16:17], v[16:17], 1.0 op_sel_hi:[1,0]
	v_pk_add_f32 v[14:15], v[14:15], 1.0 op_sel_hi:[1,0]
	v_pk_add_f32 v[10:11], v[10:11], 1.0 op_sel_hi:[1,0]
	v_pk_mul_f32 v[8:9], v[8:9], v[16:17]
	v_pk_mul_f32 v[6:7], v[6:7], v[14:15]
	v_pk_mul_f32 v[4:5], v[4:5], v[12:13]
	v_pk_mul_f32 v[2:3], v[2:3], v[10:11]
	v_mov_b64_e32 v[10:11], v[208:209]
	v_mov_b64_e32 v[12:13], v[210:211]
	v_mov_b64_e32 v[14:15], v[212:213]
	v_mov_b64_e32 v[16:17], v[214:215]
	s_branch .LBB0_906

.LBB0_906:
	v_lshl_add_u32 v0, v162, 2, 0
	v_mov_b32_e32 v22, v228
	s_add_u32 s4, s18, 0x5400000
	s_addc_u32 s5, s19, 0
	s_mov_b64 s[10:11], -1
	s_and_b64 vcc, exec, s[30:31]
	s_waitcnt lgkmcnt(0)
	v_pk_mul_f32 v[18:19], v[134:135], v[22:23] op_sel_hi:[1,0]
	v_add_u32_e32 v134, s70, v162
	v_pk_mul_f32 v[20:21], v[136:137], v[22:23] op_sel_hi:[1,0]
	v_pk_mul_f32 v[130:131], v[130:131], v[22:23] op_sel_hi:[1,0]
	v_pk_mul_f32 v[22:23], v[132:133], v[22:23] op_sel_hi:[1,0]
	v_ashrrev_i32_e32 v135, 31, v134
	v_pk_fma_f32 v[24:25], v[4:5], v[22:23], v[16:17]
	v_pk_fma_f32 v[22:23], v[2:3], v[130:131], v[14:15]
	v_lshlrev_b64 v[130:131], 10, v[134:135]
	v_pk_fma_f32 v[20:21], v[8:9], v[20:21], v[12:13]
	v_pk_fma_f32 v[18:19], v[6:7], v[18:19], v[10:11]
	v_lshl_add_u64 v[132:133], v[130:131], 0, v[148:149]
	s_cbranch_vccz .LBB0_908
	v_lshl_add_u64 v[136:137], v[132:133], 1, s[4:5]
	v_cvt_pk_bf16_f32 v164, v18, v19
	v_cvt_pk_bf16_f32 v165, v20, v21
	v_cvt_pk_bf16_f32 v166, v22, v23
	v_cvt_pk_bf16_f32 v167, v24, v25
	global_store_dwordx4 v[136:137], v[164:167], off
	s_mov_b64 s[10:11], 0

.LBB0_910:
	v_mov_b32_e32 v18, v229
	s_and_b64 vcc, exec, s[8:9]
	s_mov_b64 s[10:11], -1
	s_waitcnt lgkmcnt(0)
	v_pk_mul_f32 v[22:23], v[126:127], v[18:19] op_sel_hi:[1,0]
	v_pk_mul_f32 v[122:123], v[122:123], v[18:19] op_sel_hi:[1,0]
	v_pk_mul_f32 v[20:21], v[128:129], v[18:19] op_sel_hi:[1,0]
	v_pk_mul_f32 v[24:25], v[124:125], v[18:19] op_sel_hi:[1,0]
	v_pk_fma_f32 v[18:19], v[6:7], v[22:23], v[10:11]
	v_pk_fma_f32 v[22:23], v[2:3], v[122:123], v[14:15]
	v_add3_u32 v122, s70, v162, 16
	v_ashrrev_i32_e32 v123, 31, v122
	v_lshlrev_b64 v[122:123], 10, v[122:123]
	v_pk_fma_f32 v[20:21], v[8:9], v[20:21], v[12:13]
	v_pk_fma_f32 v[24:25], v[4:5], v[24:25], v[16:17]
	v_lshl_add_u64 v[124:125], v[122:123], 0, v[148:149]
	s_cbranch_vccnz .LBB0_912
	v_lshl_add_u64 v[136:137], v[124:125], 1, s[4:5]
	s_mov_b64 s[10:11], 0
	v_cvt_pk_bf16_f32 v126, v18, v19
	v_cvt_pk_bf16_f32 v127, v20, v21
	v_cvt_pk_bf16_f32 v128, v22, v23
	v_cvt_pk_bf16_f32 v129, v24, v25
	global_store_dwordx4 v[136:137], v[126:129], off

.LBB0_914:
	v_mov_b32_e32 v18, v230
	s_and_b64 vcc, exec, s[8:9]
	s_mov_b64 s[10:11], -1
	s_waitcnt lgkmcnt(0)
	v_pk_mul_f32 v[22:23], v[118:119], v[18:19] op_sel_hi:[1,0]
	v_pk_mul_f32 v[114:115], v[114:115], v[18:19] op_sel_hi:[1,0]
	v_pk_mul_f32 v[20:21], v[120:121], v[18:19] op_sel_hi:[1,0]
	v_pk_mul_f32 v[24:25], v[116:117], v[18:19] op_sel_hi:[1,0]
	v_pk_fma_f32 v[18:19], v[6:7], v[22:23], v[10:11]
	v_pk_fma_f32 v[22:23], v[2:3], v[114:115], v[14:15]
	v_add3_u32 v114, s70, v162, 32
	v_ashrrev_i32_e32 v115, 31, v114
	v_lshlrev_b64 v[114:115], 10, v[114:115]
	v_pk_fma_f32 v[20:21], v[8:9], v[20:21], v[12:13]
	v_pk_fma_f32 v[24:25], v[4:5], v[24:25], v[16:17]
	v_lshl_add_u64 v[116:117], v[114:115], 0, v[148:149]
	s_cbranch_vccnz .LBB0_916
	v_lshl_add_u64 v[126:127], v[116:117], 1, s[4:5]
	s_mov_b64 s[10:11], 0
	v_cvt_pk_bf16_f32 v118, v18, v19
	v_cvt_pk_bf16_f32 v119, v20, v21
	v_cvt_pk_bf16_f32 v120, v22, v23
	v_cvt_pk_bf16_f32 v121, v24, v25
	global_store_dwordx4 v[126:127], v[118:121], off

.LBB0_918:
	v_mov_b32_e32 v18, v231
	s_and_b64 vcc, exec, s[8:9]
	s_mov_b64 s[10:11], -1
	s_waitcnt lgkmcnt(0)
	v_pk_mul_f32 v[22:23], v[110:111], v[18:19] op_sel_hi:[1,0]
	v_pk_mul_f32 v[106:107], v[106:107], v[18:19] op_sel_hi:[1,0]
	v_pk_mul_f32 v[20:21], v[112:113], v[18:19] op_sel_hi:[1,0]
	v_pk_mul_f32 v[24:25], v[108:109], v[18:19] op_sel_hi:[1,0]
	v_pk_fma_f32 v[18:19], v[6:7], v[22:23], v[10:11]
	v_pk_fma_f32 v[22:23], v[2:3], v[106:107], v[14:15]
	v_add3_u32 v106, s70, v162, 48
	v_ashrrev_i32_e32 v107, 31, v106
	v_lshlrev_b64 v[106:107], 10, v[106:107]
	v_pk_fma_f32 v[20:21], v[8:9], v[20:21], v[12:13]
	v_pk_fma_f32 v[24:25], v[4:5], v[24:25], v[16:17]
	v_lshl_add_u64 v[108:109], v[106:107], 0, v[148:149]
	s_cbranch_vccnz .LBB0_920
	v_lshl_add_u64 v[118:119], v[108:109], 1, s[4:5]
	s_mov_b64 s[10:11], 0
	v_cvt_pk_bf16_f32 v110, v18, v19
	v_cvt_pk_bf16_f32 v111, v20, v21
	v_cvt_pk_bf16_f32 v112, v22, v23
	v_cvt_pk_bf16_f32 v113, v24, v25
	global_store_dwordx4 v[118:119], v[110:113], off

.LBB0_922:
	v_mov_b32_e32 v18, v232
	s_and_b64 vcc, exec, s[8:9]
	s_mov_b64 s[10:11], -1
	s_waitcnt lgkmcnt(0)
	v_pk_mul_f32 v[22:23], v[102:103], v[18:19] op_sel_hi:[1,0]
	v_pk_mul_f32 v[98:99], v[98:99], v[18:19] op_sel_hi:[1,0]
	v_pk_mul_f32 v[20:21], v[104:105], v[18:19] op_sel_hi:[1,0]
	v_pk_mul_f32 v[24:25], v[100:101], v[18:19] op_sel_hi:[1,0]
	v_pk_fma_f32 v[18:19], v[6:7], v[22:23], v[10:11]
	v_pk_fma_f32 v[22:23], v[2:3], v[98:99], v[14:15]
	v_add_u32_e32 v98, 0x80, v134
	v_ashrrev_i32_e32 v99, 31, v98
	v_lshlrev_b64 v[98:99], 10, v[98:99]
	v_pk_fma_f32 v[20:21], v[8:9], v[20:21], v[12:13]
	v_pk_fma_f32 v[24:25], v[4:5], v[24:25], v[16:17]
	v_lshl_add_u64 v[100:101], v[98:99], 0, v[148:149]
	s_cbranch_vccnz .LBB0_924
	v_lshl_add_u64 v[110:111], v[100:101], 1, s[4:5]
	s_mov_b64 s[10:11], 0
	v_cvt_pk_bf16_f32 v102, v18, v19
	v_cvt_pk_bf16_f32 v103, v20, v21
	v_cvt_pk_bf16_f32 v104, v22, v23
	v_cvt_pk_bf16_f32 v105, v24, v25
	global_store_dwordx4 v[110:111], v[102:105], off

.LBB0_926:
	v_mov_b32_e32 v18, v233
	s_and_b64 vcc, exec, s[8:9]
	s_mov_b64 s[10:11], -1
	s_waitcnt lgkmcnt(0)
	v_pk_mul_f32 v[22:23], v[94:95], v[18:19] op_sel_hi:[1,0]
	v_pk_mul_f32 v[90:91], v[90:91], v[18:19] op_sel_hi:[1,0]
	v_pk_mul_f32 v[20:21], v[96:97], v[18:19] op_sel_hi:[1,0]
	v_pk_mul_f32 v[24:25], v[92:93], v[18:19] op_sel_hi:[1,0]
	v_pk_fma_f32 v[18:19], v[6:7], v[22:23], v[10:11]
	v_pk_fma_f32 v[22:23], v[2:3], v[90:91], v[14:15]
	v_add_u32_e32 v90, 0x90, v134
	v_ashrrev_i32_e32 v91, 31, v90
	v_lshlrev_b64 v[90:91], 10, v[90:91]
	v_pk_fma_f32 v[20:21], v[8:9], v[20:21], v[12:13]
	v_pk_fma_f32 v[24:25], v[4:5], v[24:25], v[16:17]
	v_lshl_add_u64 v[92:93], v[90:91], 0, v[148:149]
	s_cbranch_vccnz .LBB0_928
	v_lshl_add_u64 v[102:103], v[92:93], 1, s[4:5]
	s_mov_b64 s[10:11], 0
	v_cvt_pk_bf16_f32 v94, v18, v19
	v_cvt_pk_bf16_f32 v95, v20, v21
	v_cvt_pk_bf16_f32 v96, v22, v23
	v_cvt_pk_bf16_f32 v97, v24, v25
	global_store_dwordx4 v[102:103], v[94:97], off

.LBB0_930:
	v_mov_b32_e32 v18, v234
	s_and_b64 vcc, exec, s[8:9]
	s_mov_b64 s[10:11], -1
	s_waitcnt lgkmcnt(0)
	v_pk_mul_f32 v[22:23], v[86:87], v[18:19] op_sel_hi:[1,0]
	v_pk_mul_f32 v[82:83], v[82:83], v[18:19] op_sel_hi:[1,0]
	v_pk_mul_f32 v[20:21], v[88:89], v[18:19] op_sel_hi:[1,0]
	v_pk_mul_f32 v[24:25], v[84:85], v[18:19] op_sel_hi:[1,0]
	v_pk_fma_f32 v[18:19], v[6:7], v[22:23], v[10:11]
	v_pk_fma_f32 v[22:23], v[2:3], v[82:83], v[14:15]
	v_add_u32_e32 v82, 0xa0, v134
	v_ashrrev_i32_e32 v83, 31, v82
	v_lshlrev_b64 v[82:83], 10, v[82:83]
	v_pk_fma_f32 v[20:21], v[8:9], v[20:21], v[12:13]
	v_pk_fma_f32 v[24:25], v[4:5], v[24:25], v[16:17]
	v_lshl_add_u64 v[84:85], v[82:83], 0, v[148:149]
	s_cbranch_vccnz .LBB0_932
	v_lshl_add_u64 v[94:95], v[84:85], 1, s[4:5]
	s_mov_b64 s[10:11], 0
	v_cvt_pk_bf16_f32 v86, v18, v19
	v_cvt_pk_bf16_f32 v87, v20, v21
	v_cvt_pk_bf16_f32 v88, v22, v23
	v_cvt_pk_bf16_f32 v89, v24, v25
	global_store_dwordx4 v[94:95], v[86:89], off

.LBB0_934:
	v_mov_b32_e32 v18, v235
	s_and_b64 vcc, exec, s[8:9]
	s_mov_b64 s[10:11], -1
	s_waitcnt lgkmcnt(0)
	v_pk_mul_f32 v[22:23], v[142:143], v[18:19] op_sel_hi:[1,0]
	s_nop 0
	v_pk_fma_f32 v[6:7], v[6:7], v[22:23], v[10:11]
	v_add_u32_e32 v10, 0xb0, v134
	v_ashrrev_i32_e32 v11, 31, v10
	v_pk_mul_f32 v[20:21], v[140:141], v[18:19] op_sel_hi:[1,0]
	v_pk_mul_f32 v[24:25], v[138:139], v[18:19] op_sel_hi:[1,0]
	v_pk_mul_f32 v[18:19], v[144:145], v[18:19] op_sel_hi:[1,0]
	v_lshlrev_b64 v[86:87], 10, v[10:11]
	v_pk_fma_f32 v[8:9], v[8:9], v[20:21], v[12:13]
	v_pk_fma_f32 v[4:5], v[4:5], v[24:25], v[16:17]
	v_pk_fma_f32 v[2:3], v[2:3], v[18:19], v[14:15]
	v_lshl_add_u64 v[10:11], v[86:87], 0, v[148:149]
	s_cbranch_vccnz .LBB0_936
	v_lshl_add_u64 v[16:17], v[10:11], 1, s[4:5]
	s_mov_b64 s[10:11], 0
	v_cvt_pk_bf16_f32 v12, v6, v7
	v_cvt_pk_bf16_f32 v13, v8, v9
	v_cvt_pk_bf16_f32 v14, v2, v3
	v_cvt_pk_bf16_f32 v15, v4, v5
	global_store_dwordx4 v[16:17], v[12:15], off

.LBB0_941:
	v_mov_b32_e32 v22, v228
	v_or_b32_e32 v94, 0x80, v148
	v_ashrrev_i32_e32 v95, 31, v94
	s_and_b64 vcc, exec, s[8:9]
	s_mov_b64 s[10:11], -1
	s_waitcnt lgkmcnt(0)
	v_pk_mul_f32 v[18:19], v[72:73], v[22:23] op_sel_hi:[1,0]
	v_pk_mul_f32 v[24:25], v[70:71], v[22:23] op_sel_hi:[1,0]
	v_pk_fma_f32 v[20:21], v[8:9], v[18:19], v[12:13]
	v_pk_fma_f32 v[18:19], v[6:7], v[24:25], v[10:11]
	v_pk_mul_f32 v[24:25], v[66:67], v[22:23] op_sel_hi:[1,0]
	v_pk_mul_f32 v[22:23], v[68:69], v[22:23] op_sel_hi:[1,0]
	v_pk_fma_f32 v[24:25], v[4:5], v[24:25], v[16:17]
	v_pk_fma_f32 v[22:23], v[2:3], v[22:23], v[14:15]
	s_cbranch_vccnz .LBB0_943
	v_lshl_add_u64 v[70:71], v[130:131], 0, v[94:95]
	v_lshl_add_u64 v[70:71], v[70:71], 1, s[4:5]
	s_mov_b64 s[10:11], 0
	v_cvt_pk_bf16_f32 v66, v18, v19
	v_cvt_pk_bf16_f32 v67, v20, v21
	v_cvt_pk_bf16_f32 v68, v22, v23
	v_cvt_pk_bf16_f32 v69, v24, v25
	global_store_dwordx4 v[70:71], v[66:69], off

.LBB0_945:
	v_mov_b32_e32 v18, v229
	s_and_b64 vcc, exec, s[8:9]
	s_mov_b64 s[10:11], -1
	s_waitcnt lgkmcnt(0)
	v_pk_mul_f32 v[20:21], v[64:65], v[18:19] op_sel_hi:[1,0]
	v_pk_mul_f32 v[22:23], v[62:63], v[18:19] op_sel_hi:[1,0]
	v_pk_mul_f32 v[24:25], v[60:61], v[18:19] op_sel_hi:[1,0]
	v_pk_mul_f32 v[58:59], v[58:59], v[18:19] op_sel_hi:[1,0]
	v_pk_fma_f32 v[20:21], v[8:9], v[20:21], v[12:13]
	v_pk_fma_f32 v[18:19], v[6:7], v[22:23], v[10:11]
	v_pk_fma_f32 v[24:25], v[4:5], v[24:25], v[16:17]
	v_pk_fma_f32 v[22:23], v[2:3], v[58:59], v[14:15]
	s_cbranch_vccnz .LBB0_947
	v_lshl_add_u64 v[62:63], v[122:123], 0, v[94:95]
	v_lshl_add_u64 v[62:63], v[62:63], 1, s[4:5]
	s_mov_b64 s[10:11], 0
	v_cvt_pk_bf16_f32 v58, v18, v19
	v_cvt_pk_bf16_f32 v59, v20, v21
	v_cvt_pk_bf16_f32 v60, v22, v23
	v_cvt_pk_bf16_f32 v61, v24, v25
	global_store_dwordx4 v[62:63], v[58:61], off

.LBB0_949:
	v_mov_b32_e32 v18, v230
	s_and_b64 vcc, exec, s[8:9]
	s_mov_b64 s[10:11], -1
	s_waitcnt lgkmcnt(0)
	v_pk_mul_f32 v[20:21], v[56:57], v[18:19] op_sel_hi:[1,0]
	v_pk_mul_f32 v[22:23], v[54:55], v[18:19] op_sel_hi:[1,0]
	v_pk_mul_f32 v[24:25], v[52:53], v[18:19] op_sel_hi:[1,0]
	v_pk_mul_f32 v[50:51], v[50:51], v[18:19] op_sel_hi:[1,0]
	v_pk_fma_f32 v[20:21], v[8:9], v[20:21], v[12:13]
	v_pk_fma_f32 v[18:19], v[6:7], v[22:23], v[10:11]
	v_pk_fma_f32 v[24:25], v[4:5], v[24:25], v[16:17]
	v_pk_fma_f32 v[22:23], v[2:3], v[50:51], v[14:15]
	s_cbranch_vccnz .LBB0_951
	v_lshl_add_u64 v[54:55], v[114:115], 0, v[94:95]
	v_lshl_add_u64 v[54:55], v[54:55], 1, s[4:5]
	s_mov_b64 s[10:11], 0
	v_cvt_pk_bf16_f32 v50, v18, v19
	v_cvt_pk_bf16_f32 v51, v20, v21
	v_cvt_pk_bf16_f32 v52, v22, v23
	v_cvt_pk_bf16_f32 v53, v24, v25
	global_store_dwordx4 v[54:55], v[50:53], off

.LBB0_953:
	v_mov_b32_e32 v18, v231
	s_and_b64 vcc, exec, s[8:9]
	s_mov_b64 s[10:11], -1
	s_waitcnt lgkmcnt(0)
	v_pk_mul_f32 v[20:21], v[48:49], v[18:19] op_sel_hi:[1,0]
	v_pk_mul_f32 v[22:23], v[46:47], v[18:19] op_sel_hi:[1,0]
	v_pk_mul_f32 v[24:25], v[44:45], v[18:19] op_sel_hi:[1,0]
	v_pk_mul_f32 v[42:43], v[42:43], v[18:19] op_sel_hi:[1,0]
	v_pk_fma_f32 v[20:21], v[8:9], v[20:21], v[12:13]
	v_pk_fma_f32 v[18:19], v[6:7], v[22:23], v[10:11]
	v_pk_fma_f32 v[24:25], v[4:5], v[24:25], v[16:17]
	v_pk_fma_f32 v[22:23], v[2:3], v[42:43], v[14:15]
	s_cbranch_vccnz .LBB0_955
	v_lshl_add_u64 v[46:47], v[106:107], 0, v[94:95]
	v_lshl_add_u64 v[46:47], v[46:47], 1, s[4:5]
	s_mov_b64 s[10:11], 0
	v_cvt_pk_bf16_f32 v42, v18, v19
	v_cvt_pk_bf16_f32 v43, v20, v21
	v_cvt_pk_bf16_f32 v44, v22, v23
	v_cvt_pk_bf16_f32 v45, v24, v25
	global_store_dwordx4 v[46:47], v[42:45], off

.LBB0_957:
	v_mov_b32_e32 v18, v232
	s_and_b64 vcc, exec, s[8:9]
	s_mov_b64 s[10:11], -1
	s_waitcnt lgkmcnt(0)
	v_pk_mul_f32 v[20:21], v[40:41], v[18:19] op_sel_hi:[1,0]
	v_pk_mul_f32 v[22:23], v[38:39], v[18:19] op_sel_hi:[1,0]
	v_pk_mul_f32 v[24:25], v[36:37], v[18:19] op_sel_hi:[1,0]
	v_pk_mul_f32 v[34:35], v[34:35], v[18:19] op_sel_hi:[1,0]
	v_pk_fma_f32 v[20:21], v[8:9], v[20:21], v[12:13]
	v_pk_fma_f32 v[18:19], v[6:7], v[22:23], v[10:11]
	v_pk_fma_f32 v[24:25], v[4:5], v[24:25], v[16:17]
	v_pk_fma_f32 v[22:23], v[2:3], v[34:35], v[14:15]
	s_cbranch_vccnz .LBB0_959
	v_lshl_add_u64 v[38:39], v[98:99], 0, v[94:95]
	v_lshl_add_u64 v[38:39], v[38:39], 1, s[4:5]
	s_mov_b64 s[10:11], 0
	v_cvt_pk_bf16_f32 v34, v18, v19
	v_cvt_pk_bf16_f32 v35, v20, v21
	v_cvt_pk_bf16_f32 v36, v22, v23
	v_cvt_pk_bf16_f32 v37, v24, v25
	global_store_dwordx4 v[38:39], v[34:37], off

.LBB0_961:
	v_mov_b32_e32 v18, v233
	s_and_b64 vcc, exec, s[8:9]
	s_mov_b64 s[10:11], -1
	s_waitcnt lgkmcnt(0)
	v_pk_mul_f32 v[20:21], v[32:33], v[18:19] op_sel_hi:[1,0]
	v_pk_mul_f32 v[22:23], v[30:31], v[18:19] op_sel_hi:[1,0]
	v_pk_mul_f32 v[24:25], v[28:29], v[18:19] op_sel_hi:[1,0]
	v_pk_mul_f32 v[26:27], v[26:27], v[18:19] op_sel_hi:[1,0]
	v_pk_fma_f32 v[20:21], v[8:9], v[20:21], v[12:13]
	v_pk_fma_f32 v[18:19], v[6:7], v[22:23], v[10:11]
	v_pk_fma_f32 v[24:25], v[4:5], v[24:25], v[16:17]
	v_pk_fma_f32 v[22:23], v[2:3], v[26:27], v[14:15]
	s_cbranch_vccnz .LBB0_963
	v_lshl_add_u64 v[30:31], v[90:91], 0, v[94:95]
	v_lshl_add_u64 v[30:31], v[30:31], 1, s[4:5]
	s_mov_b64 s[10:11], 0
	v_cvt_pk_bf16_f32 v26, v18, v19
	v_cvt_pk_bf16_f32 v27, v20, v21
	v_cvt_pk_bf16_f32 v28, v22, v23
	v_cvt_pk_bf16_f32 v29, v24, v25
	global_store_dwordx4 v[30:31], v[26:29], off

.LBB0_965:
	v_mov_b32_e32 v18, v234
	s_and_b64 vcc, exec, s[8:9]
	s_mov_b64 s[10:11], -1
	s_waitcnt lgkmcnt(0)
	v_pk_mul_f32 v[20:21], v[76:77], v[18:19] op_sel_hi:[1,0]
	v_pk_mul_f32 v[22:23], v[78:79], v[18:19] op_sel_hi:[1,0]
	v_pk_mul_f32 v[24:25], v[74:75], v[18:19] op_sel_hi:[1,0]
	v_pk_mul_f32 v[26:27], v[80:81], v[18:19] op_sel_hi:[1,0]
	v_pk_fma_f32 v[20:21], v[8:9], v[20:21], v[12:13]
	v_pk_fma_f32 v[18:19], v[6:7], v[22:23], v[10:11]
	v_pk_fma_f32 v[24:25], v[4:5], v[24:25], v[16:17]
	v_pk_fma_f32 v[22:23], v[2:3], v[26:27], v[14:15]
	s_cbranch_vccnz .LBB0_967
	v_lshl_add_u64 v[30:31], v[82:83], 0, v[94:95]
	v_lshl_add_u64 v[30:31], v[30:31], 1, s[4:5]
	s_mov_b64 s[10:11], 0
	v_cvt_pk_bf16_f32 v26, v18, v19
	v_cvt_pk_bf16_f32 v27, v20, v21
	v_cvt_pk_bf16_f32 v28, v22, v23
	v_cvt_pk_bf16_f32 v29, v24, v25
	global_store_dwordx4 v[30:31], v[26:29], off

.LBB0_969:
	v_mov_b32_e32 v0, v235
	s_and_b64 vcc, exec, s[8:9]
	s_mov_b64 s[8:9], -1
	s_waitcnt lgkmcnt(0)
	v_pk_mul_f32 v[18:19], v[152:153], v[0:1] op_sel_hi:[1,0]
	v_pk_mul_f32 v[20:21], v[154:155], v[0:1] op_sel_hi:[1,0]
	v_pk_mul_f32 v[22:23], v[146:147], v[0:1] op_sel_hi:[1,0]
	v_pk_mul_f32 v[24:25], v[156:157], v[0:1] op_sel_hi:[1,0]
	v_pk_fma_f32 v[8:9], v[8:9], v[18:19], v[12:13]
	v_pk_fma_f32 v[6:7], v[6:7], v[20:21], v[10:11]
	v_pk_fma_f32 v[4:5], v[4:5], v[22:23], v[16:17]
	v_pk_fma_f32 v[2:3], v[2:3], v[24:25], v[14:15]
	s_cbranch_vccnz .LBB0_971
	v_lshl_add_u64 v[14:15], v[86:87], 0, v[94:95]
	v_lshl_add_u64 v[14:15], v[14:15], 1, s[4:5]
	s_mov_b64 s[8:9], 0
	v_cvt_pk_bf16_f32 v10, v6, v7
	v_cvt_pk_bf16_f32 v11, v8, v9
	v_cvt_pk_bf16_f32 v12, v2, v3
	v_cvt_pk_bf16_f32 v13, v4, v5
	global_store_dwordx4 v[14:15], v[10:13], off
